# FoX tile: exp/cvt spread three per MFMA shadow through the PV MFMAs (was a VALU-only block then 9 bare MFMAs)
# speedup vs baseline: 1.0206x; 1.0084x over previous
; #define LAS3 __attribute__((address_space(3)))
; __device__ __forceinline__ unsigned cvtpk(float lo, float hi) { f32x2_t v = {lo, hi}; bf16x2_t b = __builtin_convertvector(v, bf16x2_t); return __builtin_bit_cast(unsigned, b); }
; __device__ __forceinline__ s16x4 vtr(const LAS3 unsigned char* p) { return __builtin_bit_cast(s16x4, __builtin_amdgcn_ds_read_tr16_b64_v4i16((LAS3 v4i16_t*)p)); }
; __device__ __forceinline__ void fox_unit(int b, int hh, int qb, const bf16_t* Q, const bf16_t* __restrict__ K, const bf16_t* __restrict__ V, bf16_t* O, ...
;     ...
;             for (int r = 0; r < 16; ++r) { p0[r] = __builtin_amdgcn_exp2f(p0[r]); p1[r] = __builtin_amdgcn_exp2f(p1[r]); }
;             u32x4 pw[4];
; #pragma unroll
;             for (int i = 0; i < 4; ++i) { pw[0][i] = cvtpk(p0[2 * i], p0[2 * i + 1]); pw[1][i] = cvtpk(p0[8 + 2 * i], p0[8 + 2 * i + 1]); pw[2][i] = cvtpk(p1[2 * i], p1[2 * i + 1]); pw[3][i] = cvtpk(p1[8 + 2 * i], p1[8 + 2 * i + 1]); }
;             const LAS3 unsigned char* vp = vp0 + slot * SLOTB;
; #pragma unroll
;             for (int ks = 0; ks < 4; ++ks) {
;                 const s16x4 l0 = vtr(vp + ks * 1024), h0 = vtr(vp + ks * 1024 + 512), l1 = vtr(vp + 4096 + ks * 1024), h1 = vtr(vp + 4096 + ks * 1024 + 512);
;                 const bf16x8 v0 = (bf16x8){l0[0], l0[1], l0[2], l0[3], h0[0], h0[1], h0[2], h0[3]}, v1 = (bf16x8){l1[0], l1[1], l1[2], l1[3], h1[0], h1[1], h1[2], h1[3]};
;                 const bf16x8 pf = __builtin_bit_cast(bf16x8, pw[ks]);
;                 o0 = __builtin_amdgcn_mfma_f32_32x32x16_bf16(v0, pf, o0, 0, 0, 0);
;                 o1 = __builtin_amdgcn_mfma_f32_32x32x16_bf16(v1, pf, o1, 0, 0, 0);
;                 lacc = __builtin_amdgcn_mfma_f32_32x32x16_bf16(onesA, pf, lacc, 0, 0, 0);
;             }
.LBB0_430:
	s_nop 7
	s_mov_b32 s77, s76
	s_mov_b32 s78, s76
	s_mov_b32 s79, s76
	v_mov_b64_e32 v[12:13], s[76:77]
	v_mov_b64_e32 v[14:15], s[78:79]
	v_exp_f32_e32 v82, v82
	v_exp_f32_e32 v83, v83
	v_exp_f32_e32 v84, v84
	v_exp_f32_e32 v85, v85
	v_exp_f32_e32 v86, v86
	v_exp_f32_e32 v87, v87
	v_exp_f32_e32 v88, v88
	v_exp_f32_e32 v89, v89
	v_cvt_pk_bf16_f32 v228, v82, v83
	v_cvt_pk_bf16_f32 v229, v84, v85
	v_cvt_pk_bf16_f32 v230, v86, v87
	v_cvt_pk_bf16_f32 v231, v88, v89
	s_waitcnt lgkmcnt(0)
	s_nop 0
	v_mfma_f32_32x32x16_bf16 v[34:49], v[188:191], v[228:231], v[34:49]
	v_exp_f32_e32 v90, v90
	v_exp_f32_e32 v91, v91
	v_exp_f32_e32 v92, v92
	v_mfma_f32_32x32x16_bf16 v[18:33], v[192:195], v[228:231], v[18:33]
	v_exp_f32_e32 v93, v93
	v_exp_f32_e32 v94, v94
	v_exp_f32_e32 v95, v95
	v_mfma_f32_32x32x16_bf16 v[66:81], v[12:15], v[228:231], v[66:81]
	v_exp_f32_e32 v96, v96
	v_exp_f32_e32 v97, v97
	v_cvt_pk_bf16_f32 v232, v90, v91
	v_cvt_pk_bf16_f32 v233, v92, v93
	v_cvt_pk_bf16_f32 v234, v94, v95
	v_cvt_pk_bf16_f32 v235, v96, v97
	v_exp_f32_e32 v98, v98
	v_exp_f32_e32 v99, v99
	v_mfma_f32_32x32x16_bf16 v[34:49], v[196:199], v[232:235], v[34:49]
	v_exp_f32_e32 v100, v100
	v_exp_f32_e32 v101, v101
	v_exp_f32_e32 v102, v102
	v_mfma_f32_32x32x16_bf16 v[18:33], v[200:203], v[232:235], v[18:33]
	v_exp_f32_e32 v103, v103
	v_exp_f32_e32 v104, v104
	v_exp_f32_e32 v105, v105
	v_mfma_f32_32x32x16_bf16 v[66:81], v[12:15], v[232:235], v[66:81]
	v_cvt_pk_bf16_f32 v236, v98, v99
	v_cvt_pk_bf16_f32 v237, v100, v101
	v_cvt_pk_bf16_f32 v238, v102, v103
	v_cvt_pk_bf16_f32 v239, v104, v105
	v_exp_f32_e32 v106, v106
	v_exp_f32_e32 v107, v107
	v_mfma_f32_32x32x16_bf16 v[34:49], v[204:207], v[236:239], v[34:49]
	v_exp_f32_e32 v108, v108
	v_exp_f32_e32 v109, v109
	v_exp_f32_e32 v110, v110
	v_mfma_f32_32x32x16_bf16 v[18:33], v[208:211], v[236:239], v[18:33]
	v_exp_f32_e32 v111, v111
	v_exp_f32_e32 v112, v112
	v_exp_f32_e32 v113, v113
	v_mfma_f32_32x32x16_bf16 v[66:81], v[12:15], v[236:239], v[66:81]
	v_cvt_pk_bf16_f32 v240, v106, v107
	v_cvt_pk_bf16_f32 v241, v108, v109
	v_cvt_pk_bf16_f32 v242, v110, v111
	v_cvt_pk_bf16_f32 v243, v112, v113
	s_nop 1
	v_mfma_f32_32x32x16_bf16 v[34:49], v[212:215], v[240:243], v[34:49]
	v_mfma_f32_32x32x16_bf16 v[18:33], v[216:219], v[240:243], v[18:33]
	v_mfma_f32_32x32x16_bf16 v[66:81], v[12:15], v[240:243], v[66:81]
